# plus: the 32 exec-masked per-element bias LDS reads of the attention window chunks batched into two groups of 16 unmasked reads + v_cndmask (same values)
# speedup vs baseline: 1.0390x; 1.0005x over previous
; __device__ __forceinline__ void attn_job(const Params& p, char* smem, int l, int b, int qrow0, int hp, int r) {
;     ...
;     f32x16 st[2];
; #pragma unroll
;     for (int mt = 0; mt < 2; ++mt) {
; #pragma unroll
;       for (int q = 0; q < 16; ++q) st[mt][q] = 0.f;
; #pragma unroll
;       for (int ks = 0; ks < 4; ++ks) {
;         bf16x8 a = *(const bf16x8*)&Ks[(hl * 64 + 32 * mt + ql) * 72 + 16 * ks + 8 * h5];
;         st[mt] = __builtin_amdgcn_mfma_f32_32x32x16_bf16(a, ci < 8 ? qr[ks] : qp[ks], st[mt], 0, 0, 0);
;       }
;     }
;     if (ci < 8) {
;       const int rb = (rs + ci - r + 7) * 31;
; #pragma unroll
;       for (int mt = 0; mt < 2; ++mt)
; #pragma unroll
;         for (int q = 0; q < 16; ++q) {
;           int kc = 32 * mt + (q & 3) + 8 * (q >> 2) + 4 * h5;
;           int dd = kc - cs;
;           bool valid = dd >= 0 && dd < 16;
;           float bias = rp[hl * 480 + (valid ? rb + kc - qc + 15 : 0)];
;           st[mt][q] = valid ? st[mt][q] + bias : -1e30f;
;         }
.LBB0_901:
	v_add_u32_e32 v165, v134, v160
	ds_read_b128 v[38:41], v165
	ds_read_b128 v[42:45], v165 offset:32
	s_cmp_lt_u32 s11, 8
	s_cselect_b64 s[0:1], -1, 0
	v_cndmask_b32_e64 v37, v69, v73, s[0:1]
	v_cndmask_b32_e64 v36, v68, v72, s[0:1]
	v_cndmask_b32_e64 v35, v67, v71, s[0:1]
	v_cndmask_b32_e64 v34, v66, v70, s[0:1]
	v_cndmask_b32_e64 v169, v77, v81, s[0:1]
	v_cndmask_b32_e64 v168, v76, v80, s[0:1]
	s_waitcnt lgkmcnt(0)
	v_mfma_f32_32x32x16_bf16 v[50:65], v[38:41], v[34:37], 0
	v_cndmask_b32_e64 v167, v75, v79, s[0:1]
	v_cndmask_b32_e64 v166, v74, v78, s[0:1]
	ds_read_b128 v[38:41], v165 offset:64
	ds_read_b128 v[188:191], v165 offset:4640
	v_cndmask_b32_e64 v183, v85, v89, s[0:1]
	v_cndmask_b32_e64 v182, v84, v88, s[0:1]
	v_cndmask_b32_e64 v181, v83, v87, s[0:1]
	v_mfma_f32_32x32x16_bf16 v[50:65], v[42:45], v[166:169], v[50:65]
	v_cndmask_b32_e64 v180, v82, v86, s[0:1]
	v_cndmask_b32_e64 v187, v93, v97, s[0:1]
	v_cndmask_b32_e64 v186, v92, v96, s[0:1]
	v_cndmask_b32_e64 v185, v91, v95, s[0:1]
	v_cndmask_b32_e64 v184, v90, v94, s[0:1]
	s_cmp_gt_u32 s11, 7
	s_waitcnt lgkmcnt(0)
	v_mfma_f32_32x32x16_bf16 v[50:65], v[38:41], v[180:183], v[50:65]
	ds_read_b128 v[38:41], v165 offset:96
	s_waitcnt lgkmcnt(0)
	v_mfma_f32_32x32x16_bf16 v[50:65], v[38:41], v[184:187], v[50:65]
	ds_read_b128 v[38:41], v165 offset:4608
	s_waitcnt lgkmcnt(0)
	v_mfma_f32_32x32x16_bf16 v[34:49], v[38:41], v[34:37], 0
	v_mfma_f32_32x32x16_bf16 v[34:49], v[188:191], v[166:169], v[34:49]
	ds_read_b128 v[166:169], v165 offset:4672
	s_waitcnt lgkmcnt(0)
	v_mfma_f32_32x32x16_bf16 v[34:49], v[166:169], v[180:183], v[34:49]
	ds_read_b128 v[166:169], v165 offset:4704
	s_waitcnt lgkmcnt(0)
	v_mfma_f32_32x32x16_bf16 v[34:49], v[166:169], v[184:187], v[34:49]
	s_cbranch_scc1 .LBB0_967
	v_mov_b32_e32 v167, 0xf149f2ca
	v_mov_b32_e32 v180, 0xf149f2ca
	ds_read_b32 v240, v161
	ds_read_b32 v241, v161 offset:4
	ds_read_b32 v242, v161 offset:8
	ds_read_b32 v243, v161 offset:12
	ds_read_b32 v244, v161 offset:32
	ds_read_b32 v245, v161 offset:36
	ds_read_b32 v246, v161 offset:40
	ds_read_b32 v247, v161 offset:44
	ds_read_b32 v248, v161 offset:64
	ds_read_b32 v249, v161 offset:68
	ds_read_b32 v250, v161 offset:72
	ds_read_b32 v251, v161 offset:76
	ds_read_b32 v252, v161 offset:96
	ds_read_b32 v253, v161 offset:100
	ds_read_b32 v254, v161 offset:104
	ds_read_b32 v255, v161 offset:108
	s_waitcnt lgkmcnt(0)
	v_add_f32_e32 v240, v50, v240
	v_cndmask_b32_e64 v180, v180, v240, s[4:5]
	v_add_f32_e32 v241, v51, v241
	v_cndmask_b32_e64 v167, v167, v241, s[38:39]
	v_mov_b32_e32 v165, 0xf149f2ca
	v_mov_b32_e32 v179, 0xf149f2ca
	v_add_f32_e32 v242, v52, v242
	v_cndmask_b32_e64 v179, v179, v242, s[40:41]
	v_add_f32_e32 v243, v53, v243
	v_cndmask_b32_e64 v165, v165, v243, s[42:43]
	v_mov_b32_e32 v166, 0xf149f2ca
	v_mov_b32_e32 v169, 0xf149f2ca
	v_add_f32_e32 v244, v54, v244
	v_cndmask_b32_e64 v169, v169, v244, s[44:45]
	v_add_f32_e32 v245, v55, v245
	v_cndmask_b32_e64 v166, v166, v245, s[46:47]
	v_mov_b32_e32 v168, 0xf149f2ca
	v_mov_b32_e32 v171, 0xf149f2ca
	v_add_f32_e32 v246, v56, v246
	v_cndmask_b32_e64 v171, v171, v246, s[48:49]
	v_add_f32_e32 v247, v57, v247
	v_cndmask_b32_e64 v168, v168, v247, s[50:51]
	v_mov_b32_e32 v170, 0xf149f2ca
	v_mov_b32_e32 v182, 0xf149f2ca
	v_add_f32_e32 v248, v58, v248
	v_cndmask_b32_e64 v182, v182, v248, s[52:53]
	v_add_f32_e32 v249, v59, v249
	v_cndmask_b32_e64 v170, v170, v249, s[16:17]
	v_mov_b32_e32 v181, 0xf149f2ca
	v_mov_b32_e32 v184, 0xf149f2ca
	v_add_f32_e32 v250, v60, v250
	v_cndmask_b32_e64 v184, v184, v250, s[56:57]
	v_add_f32_e32 v251, v61, v251
	v_cndmask_b32_e64 v181, v181, v251, s[58:59]
	v_mov_b32_e32 v183, 0xf149f2ca
	v_mov_b32_e32 v186, 0xf149f2ca
	v_add_f32_e32 v252, v62, v252
	v_cndmask_b32_e64 v186, v186, v252, s[60:61]
	v_add_f32_e32 v253, v63, v253
	v_cndmask_b32_e64 v183, v183, v253, s[62:63]
	v_mov_b32_e32 v185, 0xf149f2ca
	v_mov_b32_e32 v187, 0xf149f2ca
	v_add_f32_e32 v254, v64, v254
	v_cndmask_b32_e64 v187, v187, v254, s[64:65]
	v_add_f32_e32 v255, v65, v255
	v_cndmask_b32_e64 v185, v185, v255, s[66:67]
	v_mov_b32_e32 v188, 0xf149f2ca
	v_mov_b32_e32 v189, 0xf149f2ca
	ds_read_b32 v240, v161 offset:128
	ds_read_b32 v241, v161 offset:132
	ds_read_b32 v242, v161 offset:136
	ds_read_b32 v243, v161 offset:140
	ds_read_b32 v244, v161 offset:160
	ds_read_b32 v245, v161 offset:164
	ds_read_b32 v246, v161 offset:168
	ds_read_b32 v247, v161 offset:172
	ds_read_b32 v248, v161 offset:192
	ds_read_b32 v249, v161 offset:196
	ds_read_b32 v250, v161 offset:200
	ds_read_b32 v251, v161 offset:204
	ds_read_b32 v252, v161 offset:224
	ds_read_b32 v253, v161 offset:228
	ds_read_b32 v254, v161 offset:232
	ds_read_b32 v255, v161 offset:236
	s_waitcnt lgkmcnt(0)
	v_add_f32_e32 v240, v34, v240
	v_cndmask_b32_e64 v189, v189, v240, s[68:69]
	v_add_f32_e32 v241, v35, v241
	v_cndmask_b32_e64 v188, v188, v241, s[70:71]
	v_mov_b32_e32 v190, 0xf149f2ca
	v_mov_b32_e32 v191, 0xf149f2ca
	v_add_f32_e32 v242, v36, v242
	v_cndmask_b32_e64 v191, v191, v242, s[72:73]
	v_add_f32_e32 v243, v37, v243
	v_cndmask_b32_e64 v190, v190, v243, s[74:75]
	v_mov_b32_e32 v192, 0xf149f2ca
	v_mov_b32_e32 v193, 0xf149f2ca
	v_add_f32_e32 v244, v38, v244
	v_cndmask_b32_e64 v193, v193, v244, s[76:77]
	v_add_f32_e32 v245, v39, v245
	v_cndmask_b32_e64 v192, v192, v245, s[78:79]
	v_mov_b32_e32 v211, 0xf149f2ca
	v_mov_b32_e32 v212, 0xf149f2ca
	v_add_f32_e32 v246, v40, v246
	v_cndmask_b32_e64 v212, v212, v246, s[80:81]
	v_add_f32_e32 v247, v41, v247
	v_cndmask_b32_e64 v211, v211, v247, s[82:83]
	v_mov_b32_e32 v213, 0xf149f2ca
	v_mov_b32_e32 v214, 0xf149f2ca
	v_add_f32_e32 v248, v42, v248
	v_cndmask_b32_e64 v214, v214, v248, s[84:85]
	v_add_f32_e32 v249, v43, v249
	v_cndmask_b32_e64 v213, v213, v249, s[86:87]
	v_mov_b32_e32 v215, 0xf149f2ca
	v_mov_b32_e32 v216, 0xf149f2ca
	v_add_f32_e32 v250, v44, v250
	v_cndmask_b32_e64 v216, v216, v250, s[88:89]
	v_add_f32_e32 v251, v45, v251
	v_cndmask_b32_e64 v215, v215, v251, s[90:91]
	v_mov_b32_e32 v217, 0xf149f2ca
	v_mov_b32_e32 v218, 0xf149f2ca
	v_add_f32_e32 v252, v46, v252
	v_cndmask_b32_e64 v218, v218, v252, s[26:27]
	v_add_f32_e32 v253, v47, v253
	v_cndmask_b32_e64 v217, v217, v253, s[94:95]
	v_mov_b32_e32 v219, 0xf149f2ca
	v_mov_b32_e32 v220, 0xf149f2ca
	v_add_f32_e32 v254, v48, v254
	v_cndmask_b32_e64 v220, v220, v254, s[96:97]
	v_add_f32_e32 v255, v49, v255
	v_cndmask_b32_e32 v219, v219, v255, vcc
; __device__ __forceinline__ void attn_job(const Params& p, char* smem, int l, int b, int qrow0, int hp, int r) {
;     ...
;     if (ci < 8) {
;       const int rb = (rs + ci - r + 7) * 31;
; #pragma unroll
;       for (int mt = 0; mt < 2; ++mt)
; #pragma unroll
;         for (int q = 0; q < 16; ++q) {
;           int kc = 32 * mt + (q & 3) + 8 * (q >> 2) + 4 * h5;
;           int dd = kc - cs;
;           bool valid = dd >= 0 && dd < 16;
;           float bias = rp[hl * 480 + (valid ? rb + kc - qc + 15 : 0)];
;           st[mt][q] = valid ? st[mt][q] + bias : -1e30f;
;         }
;     }
.LBB0_966:
	s_branch .LBB0_968
.LBB0_967:
	s_nop 10
	v_mov_b32_e32 v219, v49
	v_mov_b32_e32 v220, v48
	v_mov_b32_e32 v217, v47
	v_mov_b32_e32 v218, v46
	v_mov_b32_e32 v215, v45
	v_mov_b32_e32 v216, v44
	v_mov_b32_e32 v213, v43
	v_mov_b32_e32 v214, v42
	v_mov_b32_e32 v211, v41
	v_mov_b32_e32 v212, v40
	v_mov_b32_e32 v192, v39
	v_mov_b32_e32 v193, v38
	v_mov_b32_e32 v190, v37
	v_mov_b32_e32 v191, v36
	v_mov_b32_e32 v188, v35
	v_mov_b32_e32 v189, v34
	v_mov_b32_e32 v185, v65
	v_mov_b32_e32 v187, v64
	v_mov_b32_e32 v183, v63
	v_mov_b32_e32 v186, v62
	v_mov_b32_e32 v181, v61
	v_mov_b32_e32 v184, v60
	v_mov_b32_e32 v170, v59
	v_mov_b32_e32 v182, v58
	v_mov_b32_e32 v168, v57
	v_mov_b32_e32 v171, v56
	v_mov_b32_e32 v166, v55
	v_mov_b32_e32 v169, v54
	v_mov_b32_e32 v165, v53
	v_mov_b32_e32 v179, v52
	v_mov_b32_e32 v167, v51
	v_mov_b32_e32 v180, v50
